# ssm_outputs staging: the three global->LDS copy loops (K table, u tile, end states) issue all their loads before one wait instead of load+vmcnt(0)+ds_write per iteration
# speedup vs baseline: 1.1154x; 1.0065x over previous
; __device__ __forceinline__ void ssm_outputs(const Params& p, int l, char* lds, unsigned* ctr, int* slot) {
;     ...
;       for (int i = tid; i < 65 * 32; i += NT) ((h16x8*)Kt)[i] = ks[i];
.LBB0_2063:
	s_movk_i32 s17, 0x61f
	s_mov_b64 s[18:19], 0x2000
	global_load_dwordx4 v[96:99], v[2:3], off
	v_lshl_add_u64 v[2:3], v[2:3], 0, s[18:19]
	global_load_dwordx4 v[100:103], v[2:3], off
	v_lshl_add_u64 v[2:3], v[2:3], 0, s[18:19]
	global_load_dwordx4 v[104:107], v[2:3], off
	v_lshl_add_u64 v[2:3], v[2:3], 0, s[18:19]
	global_load_dwordx4 v[108:111], v[2:3], off
	v_lshl_add_u64 v[2:3], v[2:3], 0, s[18:19]
	v_cmp_gt_u32_e32 vcc, 32, v38
	s_and_saveexec_b64 s[14:15], vcc
	s_cbranch_execz .Lso_k5
	global_load_dwordx4 v[112:115], v[2:3], off
	s_waitcnt vmcnt(0)
	ds_write_b128 v0, v[112:115] offset:32768
.Lso_k5:
	s_mov_b64 exec, s[14:15]
	s_waitcnt vmcnt(0)
	ds_write_b128 v0, v[96:99]
	ds_write_b128 v0, v[100:103] offset:8192
	ds_write_b128 v0, v[104:107] offset:16384
	ds_write_b128 v0, v[108:111] offset:24576

; __device__ __forceinline__ void ssm_outputs(const Params& p, int l, char* lds, unsigned* ctr, int* slot) {
;     ...
;       for (int i = tid; i < 2048; i += NT) {
;         int tk = i >> 1, hf = i & 1;
;         h16x8 v = *(const h16x8*)(P + ((size_t)b * SEQ + ct * 1024 + tk) * IWP + OFF_U + g * 16 + hf * 8);
;         *(h16x8*)(Bu + (tk >> 6) * BU_PITCH + (tk & 63) * 16 + hf * 8) = v;
;       }
.LBB0_2068:
	v_ashrrev_i32_e32 v8, 1, v3
	v_ashrrev_i32_e32 v9, 31, v8
	v_mov_b64_e32 v[4:5], s[0:1]
	v_lshl_add_u64 v[6:7], s[16:17], 0, v[8:9]
	v_mad_u64_u32 v[4:5], s[24:25], v6, s85, v[4:5]
	v_mov_b32_e32 v6, v5
	v_mad_u64_u32 v[6:7], s[24:25], v7, s85, v[6:7]
	v_lshlrev_b32_e32 v0, 1, v2
	v_mov_b32_e32 v5, v6
	v_and_b32_e32 v0, 16, v0
	v_lshl_add_u64 v[4:5], v[4:5], 0, s[92:93]
	v_lshl_add_u64 v[4:5], v[4:5], 0, v[0:1]
	v_add_co_u32_e32 v4, vcc, s91, v4
	v_lshlrev_b32_e32 v8, 5, v8
	s_nop 0
	v_addc_co_u32_e32 v5, vcc, 0, v5, vcc
	global_load_dwordx4 v[96:99], v[4:5], off offset:2560
	s_lshl_b32 s18, s85, 8
	s_mov_b32 s19, 0
	v_lshl_add_u64 v[112:113], v[4:5], 0, s[18:19]
	global_load_dwordx4 v[100:103], v[112:113], off offset:2560
	v_lshl_add_u64 v[112:113], v[112:113], 0, s[18:19]
	global_load_dwordx4 v[104:107], v[112:113], off offset:2560
	v_lshl_add_u64 v[112:113], v[112:113], 0, s[18:19]
	global_load_dwordx4 v[108:111], v[112:113], off offset:2560
	v_ashrrev_i32_e32 v9, 7, v3
	s_movk_i32 s23, 0x5ff
	v_and_b32_e32 v8, 0x7e0, v8
	v_mad_u64_u32 v[8:9], s[24:25], v9, s26, v[8:9]
	v_or_b32_e32 v0, v8, v0
	s_waitcnt vmcnt(0)
	ds_write_b128 v0, v[96:99] offset:33280
	ds_write_b128 v0, v[100:103] offset:41600
	ds_write_b128 v0, v[104:107] offset:49920
	ds_write_b128 v0, v[108:111] offset:58240
	v_mov_b32_e32 v0, s13

; __device__ __forceinline__ void ssm_outputs(const Params& p, int l, char* lds, unsigned* ctr, int* slot) {
;     ...
;       const float2* Eb = (const float2*)E + ((size_t)(b * 128) * 32 + g) * 64;
;       for (int i = tid; i < (c0 + 16) * 64; i += NT) Es[i] = Eb[(size_t)(i >> 6) * 2048 + (i & 63)];
;     }
;     __syncthreads();
;     if (w == 0) {
;       float2 at = ((const float2*)(WS(p) + O_AT))[lg * 64 + lane];
;       float sr = 0.f, si = 0.f;
; #pragma unroll 8
;       for (int c = 0; c < c0; ++c) {
;         float2 e = Es[c * 64 + lane];
.LBB0_2072:
	v_readfirstlane_b32 s18, v0
	v_ashrrev_i32_e32 v6, 6, v5
	v_ashrrev_i32_e32 v7, 31, v6
	v_lshlrev_b64 v[6:7], 14, v[6:7]
	v_lshl_add_u64 v[6:7], v[2:3], 0, v[6:7]
	s_lshr_b32 s18, s18, 9
	s_mov_b32 s16, 0x20000
	s_mov_b32 s17, 0
	global_load_dwordx2 v[96:97], v[6:7], off
	v_lshl_add_u64 v[6:7], v[6:7], 0, s[16:17]
	global_load_dwordx2 v[98:99], v[6:7], off
	v_lshl_add_u64 v[6:7], v[6:7], 0, s[16:17]
	s_cmp_le_u32 s18, 2
	s_cbranch_scc1 .Lso_ld_done
	global_load_dwordx2 v[100:101], v[6:7], off
	v_lshl_add_u64 v[6:7], v[6:7], 0, s[16:17]
	global_load_dwordx2 v[102:103], v[6:7], off
	v_lshl_add_u64 v[6:7], v[6:7], 0, s[16:17]
	s_cmp_le_u32 s18, 4
	s_cbranch_scc1 .Lso_ld_done
	global_load_dwordx2 v[104:105], v[6:7], off
	v_lshl_add_u64 v[6:7], v[6:7], 0, s[16:17]
	global_load_dwordx2 v[106:107], v[6:7], off
	v_lshl_add_u64 v[6:7], v[6:7], 0, s[16:17]
	s_cmp_le_u32 s18, 6
	s_cbranch_scc1 .Lso_ld_done
	global_load_dwordx2 v[108:109], v[6:7], off
	v_lshl_add_u64 v[6:7], v[6:7], 0, s[16:17]
	global_load_dwordx2 v[110:111], v[6:7], off
	v_lshl_add_u64 v[6:7], v[6:7], 0, s[16:17]
	s_cmp_le_u32 s18, 8
	s_cbranch_scc1 .Lso_ld_done
	global_load_dwordx2 v[112:113], v[6:7], off
	v_lshl_add_u64 v[6:7], v[6:7], 0, s[16:17]
	global_load_dwordx2 v[114:115], v[6:7], off
	v_lshl_add_u64 v[6:7], v[6:7], 0, s[16:17]
	s_cmp_le_u32 s18, 10
	s_cbranch_scc1 .Lso_ld_done
	global_load_dwordx2 v[116:117], v[6:7], off
	v_lshl_add_u64 v[6:7], v[6:7], 0, s[16:17]
	global_load_dwordx2 v[118:119], v[6:7], off
	v_lshl_add_u64 v[6:7], v[6:7], 0, s[16:17]
	s_cmp_le_u32 s18, 12
	s_cbranch_scc1 .Lso_ld_done
	global_load_dwordx2 v[120:121], v[6:7], off
	v_lshl_add_u64 v[6:7], v[6:7], 0, s[16:17]
	global_load_dwordx2 v[122:123], v[6:7], off
	v_lshl_add_u64 v[6:7], v[6:7], 0, s[16:17]
	s_cmp_le_u32 s18, 14
	s_cbranch_scc1 .Lso_ld_done
	global_load_dwordx2 v[124:125], v[6:7], off
	v_lshl_add_u64 v[6:7], v[6:7], 0, s[16:17]
	global_load_dwordx2 v[126:127], v[6:7], off
	v_lshl_add_u64 v[6:7], v[6:7], 0, s[16:17]
.Lso_ld_done:
	s_waitcnt vmcnt(0)
	ds_write_b64 v4, v[96:97]
	ds_write_b64 v4, v[98:99] offset:4096
	s_cmp_le_u32 s18, 2
	s_cbranch_scc1 .Lso_st_done
	ds_write_b64 v4, v[100:101] offset:8192
	ds_write_b64 v4, v[102:103] offset:12288
	s_cmp_le_u32 s18, 4
	s_cbranch_scc1 .Lso_st_done
	ds_write_b64 v4, v[104:105] offset:16384
	ds_write_b64 v4, v[106:107] offset:20480
	s_cmp_le_u32 s18, 6
	s_cbranch_scc1 .Lso_st_done
	ds_write_b64 v4, v[108:109] offset:24576
	ds_write_b64 v4, v[110:111] offset:28672
	s_cmp_le_u32 s18, 8
	s_cbranch_scc1 .Lso_st_done
	ds_write_b64 v4, v[112:113] offset:32768
	ds_write_b64 v4, v[114:115] offset:36864
	s_cmp_le_u32 s18, 10
	s_cbranch_scc1 .Lso_st_done
	ds_write_b64 v4, v[116:117] offset:40960
	ds_write_b64 v4, v[118:119] offset:45056
	s_cmp_le_u32 s18, 12
	s_cbranch_scc1 .Lso_st_done
	ds_write_b64 v4, v[120:121] offset:49152
	ds_write_b64 v4, v[122:123] offset:53248
	s_cmp_le_u32 s18, 14
	s_cbranch_scc1 .Lso_st_done
	ds_write_b64 v4, v[124:125] offset:57344
	ds_write_b64 v4, v[126:127] offset:61440
.Lso_st_done:
.LBB0_2073:
	s_or_b64 exec, exec, s[14:15]
	s_or_b32 s92, s21, s20
	s_waitcnt lgkmcnt(0)
	s_barrier
	s_and_saveexec_b64 s[14:15], s[8:9]
	s_cbranch_execz .LBB0_2080
	s_mov_b32 s13, 0
	s_ashr_i32 s17, s13, 31
	s_add_u32 s16, s82, s13
	s_addc_u32 s17, s83, s17
	v_lshl_or_b32 v0, s92, 6, v38
	v_lshl_add_u64 v[2:3], v[0:1], 3, s[16:17]
	v_add_co_u32_e32 v2, vcc, 0xa019000, v2
	s_cmp_lg_u32 s22, 0
	s_nop 0
	v_addc_co_u32_e32 v3, vcc, 0, v3, vcc
	global_load_dwordx2 v[2:3], v[2:3], off
	s_cbranch_scc0 .LBB0_2105
	s_waitcnt vmcnt(0)
	v_pk_mov_b32 v[4:5], v[2:3], v[2:3] op_sel:[1,0]
	s_lshl_b32 s13, s22, 13
	v_mov_b32_e32 v6, 0
	s_mov_b32 s16, 0
	v_mov_b32_e32 v0, 0
